# v36 + FoX in-loop: waves 1-7 issue their (unused) forget-gate load as a one-line broadcast instead of a 64-row gather
# baseline (speedup 1.0000x reference)
; #define ATT_STORE(S, buf) do { LAS unsigned char* sb_ = lds + (buf) * BUFB; \
;         *(LAS u32x4*)(sb_ + kwoff) = kreg##S; \
;         if (TY == 2 && tid < 256) *(LAS u32x4*)(sb_ + kwoff2) = kreg2##S; \
;         *(LAS u32x4*)(sb_ + KBYTES + (ki * VSTR + kc * 8) * 2) = vreg##S; \
;         if (TY == 1 && tid < 64) *(LAS float*)(sb_ + KBYTES + VBYTES + tid * 4) = freg##S; } while (0)
; template <int TY> __device__ __forceinline__ void attn_unit(LAS unsigned char* lds, const AttnArgs& a, int b, int h, int qt, int wave_s) {
;     ...
;     ATT_LOAD(A, J0);
;     ATT_STORE(A, 0);
;     ATT_LOAD(B, J0 < J1 ? J0 + 1 : J1);
;     __syncthreads();
;     const int koff = (fr * 64 + fq * 16) ^ ((fr >> 3) << 5);
;     const int voff = KBYTES + ((4 * fq + (fr >> 2)) * VSTR + 4 * (fr & 3)) * 2;
;     const int ewlo = eq0 + 32 * wv, ewhi = ewlo + 31;
.LBB0_758:
	s_and_b64 vcc, exec, s[6:7]
	s_cbranch_vccnz .LBB0_790
	s_add_i32 s21, s17, 31
	s_add_u32 s6, s82, s8
	s_addc_u32 s7, s83, 0
	s_add_i32 s8, s62, s12
	v_add_u32_e32 v1, s8, v168
	v_or_b32_e32 v144, s19, v190
	v_mov_b32_e32 v232, s19
	v_cndmask_b32_e64 v144, v232, v144, s[88:89]
	v_sub_u32_e32 v145, v1, v176
	s_mov_b32 s22, 5
	s_movk_i32 s23, 0xff
	s_branch .LBB0_763
